# grid barrier: non-leader workgroups poll the global release generation directly instead of waiting for their XCD leader to forward it (one hop fewer per barrier)
# speedup vs baseline: 1.0058x; 1.0058x over previous
; __device__ __forceinline__ unsigned xb_ld(unsigned* p)              { return __hip_atomic_load(p, __ATOMIC_RELAXED, __HIP_MEMORY_SCOPE_AGENT); }
; __device__ __forceinline__ unsigned xb_add(unsigned* p, unsigned v) { return __hip_atomic_fetch_add(p, v, __ATOMIC_RELAXED, __HIP_MEMORY_SCOPE_AGENT); }
; #define XB_SPIN(cond, bar) do { unsigned _sp = 0; while (cond) { __builtin_amdgcn_s_sleep(1); \
;     if ((++_sp & 255u) == 0u) { if (xb_ld(&(bar)[XB_TMO])) break; if (_sp > XB_SPIN_CAP) { atomicAdd(&(bar)[XB_TMO], 1u); break; } } } } while (0)
; __device__ __forceinline__ void xcd_barrier(const XcdBarrier& b) {
;     ...
;         const unsigned old = xb_add(&bar[XB_XSUB(b.x)], 1u);
;         const unsigned gen = old / nloc;
;         if (old + 1u == (gen + 1u) * nloc) {
;             __builtin_amdgcn_fence(__ATOMIC_RELEASE, "agent");
;             asm volatile("s_waitcnt vmcnt(0)" ::: "memory");
;             const unsigned og = xb_add(&bar[XB_TOP], 1u);
;             const unsigned tg = og / nx;
;             if (og + 1u == (tg + 1u) * nx) xb_add(&bar[XB_TOPGEN], 1u);
;             else XB_SPIN(xb_ld(&bar[XB_TOPGEN]) == tg, bar);
;             __builtin_amdgcn_fence(__ATOMIC_ACQUIRE, "agent");
;             xb_add(&bar[XB_XGEN(b.x)], 1u);
;             asm volatile("s_waitcnt vmcnt(0)" ::: "memory");
;         } else {
;             XB_SPIN(xb_ld(&bar[XB_XGEN(b.x)]) == gen, bar);
;             __builtin_amdgcn_fence(__ATOMIC_ACQUIRE, "agent");
;             asm volatile("s_waitcnt vmcnt(0)" ::: "memory");
.LBB0_402:
	v_readlane_b32 s2, v254, 45
	s_lshl_b32 s96, s2, 6
	s_lshl_b64 s[2:3], s[96:97], 2
	s_add_u32 s8, s70, s2
	s_addc_u32 s9, s71, s3
	v_mov_b32_e32 v1, 0x1000
	v_mov_b32_e32 v3, 1
	global_atomic_add v3, v1, v3, s[8:9] offset:1024 sc0
	v_cvt_f32_u32_e32 v1, v2
	v_sub_u32_e32 v4, 0, v2
	v_rcp_iflag_f32_e32 v1, v1
	s_nop 0
	v_mul_f32_e32 v1, 0x4f7ffffe, v1
	v_cvt_u32_f32_e32 v1, v1
	v_mul_lo_u32 v4, v4, v1
	v_mul_hi_u32 v4, v1, v4
	v_add_u32_e32 v1, v1, v4
	s_waitcnt vmcnt(0)
	v_mul_hi_u32 v1, v3, v1
	v_mul_lo_u32 v4, v1, v2
	v_sub_u32_e32 v4, v3, v4
	v_add_u32_e32 v5, 1, v1
	v_cmp_ge_u32_e32 vcc, v4, v2
	v_add_u32_e32 v3, 1, v3
	s_nop 0
	v_cndmask_b32_e32 v1, v1, v5, vcc
	v_sub_u32_e32 v5, v4, v2
	v_cndmask_b32_e32 v4, v4, v5, vcc
	v_add_u32_e32 v5, 1, v1
	v_cmp_ge_u32_e32 vcc, v4, v2
	s_nop 1
	v_cndmask_b32_e32 v1, v1, v5, vcc
	v_mul_lo_u32 v4, v2, v1
	v_add_u32_e32 v2, v4, v2
	v_cmp_ne_u32_e32 vcc, v3, v2
	s_and_saveexec_b64 s[2:3], vcc
	s_xor_b64 s[10:11], exec, s[2:3]
	v_readlane_b32 s82, v254, 54
	s_movk_i32 s83, 0x1000
	s_cbranch_execz .LBB0_416
	s_waitcnt lgkmcnt(0)
	v_mov_b32_e32 v0, 0x3500
	global_load_dword v0, v0, s[70:71] sc1
	s_add_u32 s14, s70, 0x3500
	s_addc_u32 s15, s71, 0
	s_waitcnt vmcnt(0)
	v_cmp_eq_u32_e32 vcc, v0, v1
	s_and_saveexec_b64 s[12:13], vcc
	s_cbranch_execz .LBB0_415
	s_mov_b32 s5, 1
	s_mov_b64 s[16:17], 0
	s_branch .LBB0_406
